# P1 w_in and mem K/V epilogues: 8 rstd loads hoisted to epilogue start, per-group vmcnt(0) (which also drained the previous group's stores) removed
# speedup vs baseline: 1.0013x; 1.0013x over previous
.LBB0_211:
	v_mov_b32_e32 v132, v136
	s_lshl_b32 s0, s0, 8
	v_readlane_b32 s72, v254, 20
	v_ashrrev_i32_e32 v128, 2, v132
	v_and_b32_e32 v128, 0xffffffc0, v128
	v_and_or_b32 v129, v132, 15, s0
	v_add_u32_e32 v128, v129, v128
	v_ashrrev_i32_e32 v129, 31, v128
	v_readlane_b32 s78, v254, 26
	v_readlane_b32 s79, v254, 27
	v_readlane_b32 s73, v254, 21
	v_readlane_b32 s74, v254, 22
	v_lshl_add_u64 v[130:131], v[128:129], 2, s[78:79]
	global_load_dword v144, v[130:131], off
	global_load_dword v170, v[130:131], off offset:64
	global_load_dword v171, v[130:131], off offset:128
	global_load_dword v172, v[130:131], off offset:192
	global_load_dword v173, v[130:131], off offset:512
	global_load_dword v174, v[130:131], off offset:576
	global_load_dword v175, v[130:131], off offset:640
	global_load_dword v176, v[130:131], off offset:704
	v_readlane_b32 s75, v254, 23
	v_readlane_b32 s76, v254, 24
	v_readlane_b32 s77, v254, 25
	v_readlane_b32 s80, v254, 28
	v_readlane_b32 s81, v254, 29
	v_readlane_b32 s82, v254, 30
	v_readlane_b32 s83, v254, 31
	v_readlane_b32 s84, v254, 32
	v_readlane_b32 s85, v254, 33
	v_readlane_b32 s86, v254, 34
	v_readlane_b32 s87, v254, 35
	v_lshrrev_b32_e32 v132, 1, v132
	v_and_b32_e32 v145, 0x78, v132
	v_readlane_b32 s72, v254, 52
	v_lshl_or_b32 v138, s51, 8, v145
	v_readlane_b32 s76, v254, 56
	v_readlane_b32 s77, v254, 57
	s_movk_i32 s0, 0x3ff
	v_lshlrev_b64 v[134:135], 12, v[128:129]
	v_lshl_add_u64 v[132:133], v[138:139], 2, s[76:77]
	v_cmp_lt_i32_e32 vcc, s0, v138
	v_lshl_add_u64 v[146:147], v[132:133], 0, v[134:135]
	v_readlane_b32 s73, v254, 53
	v_readlane_b32 s74, v254, 54
	v_readlane_b32 s75, v254, 55
	v_readlane_b32 s78, v254, 58
	v_readlane_b32 s79, v254, 59
	v_readlane_b32 s80, v254, 60
	v_readlane_b32 s81, v254, 61
	v_readlane_b32 s82, v254, 62
	v_readlane_b32 s83, v254, 63
	v_readlane_b32 s84, v255, 0
	v_readlane_b32 s85, v255, 1
	v_readlane_b32 s86, v255, 2
	v_readlane_b32 s87, v255, 3
	s_waitcnt vmcnt(0)
	v_pk_mul_f32 v[126:127], v[126:127], v[144:145] op_sel_hi:[1,0]
	v_pk_mul_f32 v[124:125], v[124:125], v[144:145] op_sel_hi:[1,0]
	v_pk_mul_f32 v[122:123], v[122:123], v[144:145] op_sel_hi:[1,0]
	v_pk_mul_f32 v[120:121], v[120:121], v[144:145] op_sel_hi:[1,0]
	s_and_saveexec_b64 s[0:1], vcc
	s_xor_b64 s[0:1], exec, s[0:1]
	s_cbranch_execz .LBB0_213
	global_store_dwordx4 v[146:147], v[124:127], off offset:-4096
	global_store_dwordx4 v[146:147], v[120:123], off offset:-4080

.LBB0_219:
	s_or_b64 exec, exec, s[4:5]
	v_mov_b32_e32 v114, v170
	v_or_b32_e32 v118, 16, v128
	v_ashrrev_i32_e32 v119, 31, v118
	v_lshlrev_b64 v[116:117], 12, v[118:119]
	v_lshl_add_u64 v[112:113], v[132:133], 0, v[116:117]
	v_pk_mul_f32 v[110:111], v[110:111], v[114:115] op_sel_hi:[1,0]
	v_pk_mul_f32 v[108:109], v[108:109], v[114:115] op_sel_hi:[1,0]
	v_pk_mul_f32 v[106:107], v[106:107], v[114:115] op_sel_hi:[1,0]
	v_pk_mul_f32 v[104:105], v[104:105], v[114:115] op_sel_hi:[1,0]
	s_and_saveexec_b64 s[4:5], vcc
	s_xor_b64 s[4:5], exec, s[4:5]
	s_cbranch_execz .LBB0_221
	global_store_dwordx4 v[112:113], v[108:111], off offset:-4096
	global_store_dwordx4 v[112:113], v[104:107], off offset:-4080

.LBB0_227:
	s_or_b64 exec, exec, s[4:5]
	v_mov_b32_e32 v98, v171
	v_or_b32_e32 v102, 32, v128
	v_ashrrev_i32_e32 v103, 31, v102
	v_lshlrev_b64 v[100:101], 12, v[102:103]
	v_lshl_add_u64 v[96:97], v[132:133], 0, v[100:101]
	v_pk_mul_f32 v[94:95], v[94:95], v[98:99] op_sel_hi:[1,0]
	v_pk_mul_f32 v[92:93], v[92:93], v[98:99] op_sel_hi:[1,0]
	v_pk_mul_f32 v[90:91], v[90:91], v[98:99] op_sel_hi:[1,0]
	v_pk_mul_f32 v[88:89], v[88:89], v[98:99] op_sel_hi:[1,0]
	s_and_saveexec_b64 s[4:5], vcc
	s_xor_b64 s[4:5], exec, s[4:5]
	s_cbranch_execz .LBB0_229
	global_store_dwordx4 v[96:97], v[92:95], off offset:-4096
	global_store_dwordx4 v[96:97], v[88:91], off offset:-4080

.LBB0_235:
	s_or_b64 exec, exec, s[4:5]
	v_mov_b32_e32 v82, v172
	v_or_b32_e32 v86, 48, v128
	v_ashrrev_i32_e32 v87, 31, v86
	v_lshlrev_b64 v[84:85], 12, v[86:87]
	v_lshl_add_u64 v[80:81], v[132:133], 0, v[84:85]
	v_pk_mul_f32 v[78:79], v[78:79], v[82:83] op_sel_hi:[1,0]
	v_pk_mul_f32 v[76:77], v[76:77], v[82:83] op_sel_hi:[1,0]
	v_pk_mul_f32 v[74:75], v[74:75], v[82:83] op_sel_hi:[1,0]
	v_pk_mul_f32 v[72:73], v[72:73], v[82:83] op_sel_hi:[1,0]
	s_and_saveexec_b64 s[4:5], vcc
	s_xor_b64 s[4:5], exec, s[4:5]
	s_cbranch_execz .LBB0_237
	global_store_dwordx4 v[80:81], v[76:79], off offset:-4096
	global_store_dwordx4 v[80:81], v[72:75], off offset:-4080

.LBB0_243:
	s_or_b64 exec, exec, s[4:5]
	v_mov_b32_e32 v66, v173
	v_add_u32_e32 v70, 0x80, v128
	v_ashrrev_i32_e32 v71, 31, v70
	v_lshlrev_b64 v[68:69], 12, v[70:71]
	v_lshl_add_u64 v[64:65], v[132:133], 0, v[68:69]
	v_pk_mul_f32 v[62:63], v[62:63], v[66:67] op_sel_hi:[1,0]
	v_pk_mul_f32 v[60:61], v[60:61], v[66:67] op_sel_hi:[1,0]
	v_pk_mul_f32 v[58:59], v[58:59], v[66:67] op_sel_hi:[1,0]
	v_pk_mul_f32 v[56:57], v[56:57], v[66:67] op_sel_hi:[1,0]
	s_and_saveexec_b64 s[4:5], vcc
	s_xor_b64 s[4:5], exec, s[4:5]
	s_cbranch_execz .LBB0_245
	global_store_dwordx4 v[64:65], v[60:63], off offset:-4096
	global_store_dwordx4 v[64:65], v[56:59], off offset:-4080

.LBB0_251:
	s_or_b64 exec, exec, s[4:5]
	v_mov_b32_e32 v50, v174
	v_add_u32_e32 v54, 0x90, v128
	v_ashrrev_i32_e32 v55, 31, v54
	v_lshlrev_b64 v[52:53], 12, v[54:55]
	v_lshl_add_u64 v[48:49], v[132:133], 0, v[52:53]
	v_pk_mul_f32 v[46:47], v[46:47], v[50:51] op_sel_hi:[1,0]
	v_pk_mul_f32 v[44:45], v[44:45], v[50:51] op_sel_hi:[1,0]
	v_pk_mul_f32 v[42:43], v[42:43], v[50:51] op_sel_hi:[1,0]
	v_pk_mul_f32 v[40:41], v[40:41], v[50:51] op_sel_hi:[1,0]
	s_and_saveexec_b64 s[4:5], vcc
	s_xor_b64 s[4:5], exec, s[4:5]
	s_cbranch_execz .LBB0_253
	global_store_dwordx4 v[48:49], v[44:47], off offset:-4096
	global_store_dwordx4 v[48:49], v[40:43], off offset:-4080

.LBB0_259:
	s_or_b64 exec, exec, s[4:5]
	v_mov_b32_e32 v34, v175
	v_add_u32_e32 v38, 0xa0, v128
	v_ashrrev_i32_e32 v39, 31, v38
	v_lshlrev_b64 v[36:37], 12, v[38:39]
	v_lshl_add_u64 v[32:33], v[132:133], 0, v[36:37]
	v_pk_mul_f32 v[30:31], v[30:31], v[34:35] op_sel_hi:[1,0]
	v_pk_mul_f32 v[28:29], v[28:29], v[34:35] op_sel_hi:[1,0]
	v_pk_mul_f32 v[26:27], v[26:27], v[34:35] op_sel_hi:[1,0]
	v_pk_mul_f32 v[24:25], v[24:25], v[34:35] op_sel_hi:[1,0]
	s_and_saveexec_b64 s[4:5], vcc
	s_xor_b64 s[4:5], exec, s[4:5]
	s_cbranch_execz .LBB0_261
	global_store_dwordx4 v[32:33], v[28:31], off offset:-4096
	global_store_dwordx4 v[32:33], v[24:27], off offset:-4080

.LBB0_267:
	s_or_b64 exec, exec, s[4:5]
	v_mov_b32_e32 v18, v176
	v_add_u32_e32 v22, 0xb0, v128
	v_ashrrev_i32_e32 v23, 31, v22
	v_lshlrev_b64 v[20:21], 12, v[22:23]
	v_lshl_add_u64 v[16:17], v[132:133], 0, v[20:21]
	v_pk_mul_f32 v[14:15], v[14:15], v[18:19] op_sel_hi:[1,0]
	v_pk_mul_f32 v[12:13], v[12:13], v[18:19] op_sel_hi:[1,0]
	v_pk_mul_f32 v[10:11], v[10:11], v[18:19] op_sel_hi:[1,0]
	v_pk_mul_f32 v[8:9], v[8:9], v[18:19] op_sel_hi:[1,0]
	s_and_saveexec_b64 s[4:5], vcc
	s_xor_b64 s[4:5], exec, s[4:5]
	s_cbranch_execz .LBB0_269
	global_store_dwordx4 v[16:17], v[12:15], off offset:-4096
	global_store_dwordx4 v[16:17], v[8:11], off offset:-4080

.LBB0_283:
	v_mov_b32_e32 v157, v136
	v_readlane_b32 s72, v254, 20
	v_and_b32_e32 v132, 15, v157
	v_ashrrev_i32_e32 v128, 2, v157
	v_and_b32_e32 v128, 0xffffffc0, v128
	v_lshl_or_b32 v129, s4, 8, v132
	v_add_u32_e32 v140, v129, v128
	v_ashrrev_i32_e32 v141, 31, v140
	v_readlane_b32 s76, v254, 24
	v_readlane_b32 s77, v254, 25
	v_lshrrev_b32_e32 v129, 1, v157
	v_and_b32_e32 v160, 0x78, v129
	v_lshl_add_u64 v[148:149], v[140:141], 2, s[76:77]
	global_load_dword v150, v[148:149], off
	global_load_dword v170, v[148:149], off offset:64
	global_load_dword v171, v[148:149], off offset:128
	global_load_dword v172, v[148:149], off offset:192
	global_load_dword v173, v[148:149], off offset:512
	global_load_dword v174, v[148:149], off offset:576
	global_load_dword v175, v[148:149], off offset:640
	global_load_dword v176, v[148:149], off offset:704
	v_lshl_or_b32 v128, s0, 8, v160
	v_and_b32_e32 v158, 8, v129
	v_ashrrev_i32_e32 v129, 31, v128
	v_add_u32_e32 v130, 0xfffffc00, v128
	v_lshl_add_u64 v[146:147], v[128:129], 2, s[40:41]
	v_add_u32_e32 v128, 0xfffffc80, v128
	v_ashrrev_i32_e32 v130, 4, v130
	v_ashrrev_i32_e32 v128, 4, v128
	s_cmp_gt_i32 s0, 3
	v_ashrrev_i32_e32 v131, 31, v130
	v_ashrrev_i32_e32 v129, 31, v128
	s_cselect_b64 s[4:5], -1, 0
	s_cmp_lt_i32 s0, 4
	v_lshlrev_b64 v[144:145], 10, v[130:131]
	v_lshlrev_b64 v[142:143], 10, v[128:129]
	s_mov_b64 s[18:19], -1
	v_lshlrev_b32_e32 v159, 4, v132
	v_cmp_lt_i32_e32 vcc, s28, v140
	v_readlane_b32 s73, v254, 21
	v_readlane_b32 s74, v254, 22
	v_readlane_b32 s75, v254, 23
	v_readlane_b32 s78, v254, 26
	v_readlane_b32 s79, v254, 27
	v_readlane_b32 s80, v254, 28
	v_readlane_b32 s81, v254, 29
	v_readlane_b32 s82, v254, 30
	v_readlane_b32 s83, v254, 31
	v_readlane_b32 s84, v254, 32
	v_readlane_b32 s85, v254, 33
	v_readlane_b32 s86, v254, 34
	v_readlane_b32 s87, v254, 35
	s_cbranch_scc1 .LBB0_293
	v_add_u32_e32 v138, 0xffffc000, v140
	v_lshlrev_b64 v[152:153], 11, v[138:139]
	s_waitcnt vmcnt(0)
	v_pk_mul_f32 v[130:131], v[118:119], v[150:151] op_sel_hi:[1,0]
	v_pk_mul_f32 v[128:129], v[116:117], v[150:151] op_sel_hi:[1,0]
	v_pk_mul_f32 v[134:135], v[114:115], v[150:151] op_sel_hi:[1,0]
	v_pk_mul_f32 v[132:133], v[112:113], v[150:151] op_sel_hi:[1,0]
	v_lshl_add_u64 v[152:153], v[146:147], 0, v[152:153]
	s_and_saveexec_b64 s[18:19], vcc
	s_xor_b64 s[18:19], exec, s[18:19]
	s_cbranch_execz .LBB0_286
	global_store_dwordx4 v[152:153], v[128:131], off offset:-4096
	global_store_dwordx4 v[152:153], v[132:135], off offset:-4080

.LBB0_297:
	v_mov_b32_e32 v122, v170
	v_or_b32_e32 v120, 16, v140
	v_cndmask_b32_e64 v112, 0, 1, s[4:5]
	v_ashrrev_i32_e32 v121, 31, v120
	s_mov_b64 s[18:19], -1
	v_cmp_ne_u32_e64 s[0:1], 1, v112
	s_andn2_b64 vcc, exec, s[4:5]
	v_cmp_lt_i32_e64 s[4:5], s28, v120
	s_cbranch_vccnz .LBB0_307
	v_add_u32_e32 v138, 0xffffc010, v140
	v_lshlrev_b64 v[124:125], 11, v[138:139]
	v_pk_mul_f32 v[114:115], v[102:103], v[122:123] op_sel_hi:[1,0]
	v_pk_mul_f32 v[112:113], v[100:101], v[122:123] op_sel_hi:[1,0]
	v_pk_mul_f32 v[118:119], v[98:99], v[122:123] op_sel_hi:[1,0]
	v_pk_mul_f32 v[116:117], v[96:97], v[122:123] op_sel_hi:[1,0]
	v_lshl_add_u64 v[124:125], v[146:147], 0, v[124:125]
	s_and_saveexec_b64 s[18:19], s[4:5]
	s_xor_b64 s[18:19], exec, s[18:19]
	s_cbranch_execz .LBB0_300
	global_store_dwordx4 v[124:125], v[112:115], off offset:-4096
	global_store_dwordx4 v[124:125], v[116:119], off offset:-4080

.LBB0_307:
	s_and_b64 vcc, exec, s[18:19]
	s_cbranch_vccz .LBB0_311
	v_mul_f32_e32 v108, v108, v122
	v_mul_f32_e32 v109, v109, v122
	v_mul_f32_e32 v108, 0xbfb8aa3b, v108
	v_mul_f32_e32 v109, 0xbfb8aa3b, v109
	v_exp_f32_e32 v108, v108
	v_exp_f32_e32 v109, v109
	v_mul_f32_e32 v104, v104, v122
	v_mul_f32_e32 v105, v105, v122
	v_mul_f32_e32 v104, 0xbfb8aa3b, v104
	v_mul_f32_e32 v105, 0xbfb8aa3b, v105
	v_exp_f32_e32 v104, v104
	v_add_f32_e32 v108, 1.0, v108
	v_add_f32_e32 v109, 1.0, v109
	v_exp_f32_e32 v105, v105
	v_rcp_f32_e32 v108, v108
	v_rcp_f32_e32 v109, v109
	v_mul_f32_e32 v106, v106, v122
	v_add_f32_e32 v104, 1.0, v104
	v_pk_mul_f32 v[100:101], v[100:101], v[122:123] op_sel_hi:[1,0]
	v_add_f32_e32 v105, 1.0, v105
	v_mul_f32_e32 v106, 0xbfb8aa3b, v106
	v_rcp_f32_e32 v104, v104
	v_pk_mul_f32 v[100:101], v[100:101], v[108:109]
	v_rcp_f32_e32 v105, v105
	v_mul_f32_e32 v108, v110, v122
	v_exp_f32_e32 v106, v106
	v_mul_f32_e32 v108, 0xbfb8aa3b, v108
	v_exp_f32_e32 v108, v108
	v_pk_mul_f32 v[96:97], v[96:97], v[122:123] op_sel_hi:[1,0]
	v_pk_mul_f32 v[102:103], v[102:103], v[122:123] op_sel_hi:[1,0]
	v_pk_mul_f32 v[96:97], v[96:97], v[104:105]
	v_add_f32_e32 v105, 1.0, v106
	v_mul_f32_e32 v106, v111, v122
	v_mul_f32_e32 v106, 0xbfb8aa3b, v106
	v_add_f32_e32 v104, 1.0, v108
	v_exp_f32_e32 v108, v106
	v_mul_f32_e32 v106, v107, v122
	v_mul_f32_e32 v106, 0xbfb8aa3b, v106
	v_exp_f32_e32 v107, v106
	v_rcp_f32_e32 v106, v105
	v_add_f32_e32 v105, 1.0, v108
	v_rcp_f32_e32 v104, v104
	v_rcp_f32_e32 v105, v105
	v_add_f32_e32 v107, 1.0, v107
	v_rcp_f32_e32 v107, v107
	v_pk_mul_f32 v[98:99], v[98:99], v[122:123] op_sel_hi:[1,0]
	v_pk_mul_f32 v[102:103], v[102:103], v[104:105]
	v_lshlrev_b64 v[104:105], 10, v[120:121]
	v_pk_mul_f32 v[98:99], v[98:99], v[106:107]
	v_lshl_add_u64 v[108:109], v[130:131], 0, v[104:105]
	v_cmp_lt_i32_e32 vcc, s28, v120
	v_cvt_pk_bf16_f32 v104, v100, v101
	v_cvt_pk_bf16_f32 v105, v102, v103
	v_cvt_pk_bf16_f32 v106, v96, v97
	v_cvt_pk_bf16_f32 v107, v98, v99
	global_store_dwordx4 v[108:109], v[104:107], off
	s_and_saveexec_b64 s[4:5], vcc
	s_cbranch_execz .LBB0_310
	v_add_u32_e32 v104, 0xffffc010, v140
	v_and_b32_e32 v105, 3, v157
	v_lshrrev_b32_e32 v104, 2, v104
	v_add_u32_e32 v138, 26, v105
	v_mad_u64_u32 v[104:105], s[18:19], v104, 30, v[138:139]
	v_lshlrev_b64 v[104:105], 11, v[104:105]
	v_lshl_add_u64 v[104:105], v[128:129], 0, v[104:105]
	global_store_dwordx4 v[104:105], v[100:103], off
	global_store_dwordx4 v[104:105], v[96:99], off offset:16

.LBB0_311:
	v_mov_b32_e32 v106, v171
	v_or_b32_e32 v104, 32, v140
	v_ashrrev_i32_e32 v105, 31, v104
	s_mov_b64 s[18:19], -1
	s_and_b64 vcc, exec, s[0:1]
	v_cmp_lt_i32_e64 s[4:5], s28, v104
	s_cbranch_vccnz .LBB0_321
	v_add_u32_e32 v138, 0xffffc020, v140
	v_lshlrev_b64 v[108:109], 11, v[138:139]
	v_pk_mul_f32 v[98:99], v[86:87], v[106:107] op_sel_hi:[1,0]
	v_pk_mul_f32 v[96:97], v[84:85], v[106:107] op_sel_hi:[1,0]
	v_pk_mul_f32 v[102:103], v[82:83], v[106:107] op_sel_hi:[1,0]
	v_pk_mul_f32 v[100:101], v[80:81], v[106:107] op_sel_hi:[1,0]
	v_lshl_add_u64 v[108:109], v[146:147], 0, v[108:109]
	s_and_saveexec_b64 s[18:19], s[4:5]
	s_xor_b64 s[18:19], exec, s[18:19]
	s_cbranch_execz .LBB0_314
	global_store_dwordx4 v[108:109], v[96:99], off offset:-4096
	global_store_dwordx4 v[108:109], v[100:103], off offset:-4080

.LBB0_321:
	v_readlane_b32 s72, v254, 52
	v_readlane_b32 s78, v254, 58
	v_readlane_b32 s79, v254, 59
	s_and_b64 vcc, exec, s[18:19]
	v_readlane_b32 s73, v254, 53
	v_lshl_add_u64 v[96:97], v[132:133], 2, s[78:79]
	v_readlane_b32 s74, v254, 54
	v_readlane_b32 s75, v254, 55
	v_readlane_b32 s76, v254, 56
	v_readlane_b32 s77, v254, 57
	v_readlane_b32 s80, v254, 60
	v_readlane_b32 s81, v254, 61
	v_readlane_b32 s82, v254, 62
	v_readlane_b32 s83, v254, 63
	v_readlane_b32 s84, v255, 0
	v_readlane_b32 s85, v255, 1
	v_readlane_b32 s86, v255, 2
	v_readlane_b32 s87, v255, 3
	s_cbranch_vccz .LBB0_329
	v_mul_f32_e32 v92, v92, v106
	v_mul_f32_e32 v93, v93, v106
	v_mul_f32_e32 v92, 0xbfb8aa3b, v92
	v_mul_f32_e32 v93, 0xbfb8aa3b, v93
	v_exp_f32_e32 v92, v92
	v_exp_f32_e32 v93, v93
	v_mul_f32_e32 v88, v88, v106
	v_mul_f32_e32 v89, v89, v106
	v_mul_f32_e32 v88, 0xbfb8aa3b, v88
	v_mul_f32_e32 v89, 0xbfb8aa3b, v89
	v_exp_f32_e32 v88, v88
	v_add_f32_e32 v92, 1.0, v92
	v_add_f32_e32 v93, 1.0, v93
	v_exp_f32_e32 v89, v89
	v_rcp_f32_e32 v92, v92
	v_rcp_f32_e32 v93, v93
	v_mul_f32_e32 v90, v90, v106
	v_add_f32_e32 v88, 1.0, v88
	v_pk_mul_f32 v[84:85], v[84:85], v[106:107] op_sel_hi:[1,0]
	v_add_f32_e32 v89, 1.0, v89
	v_mul_f32_e32 v90, 0xbfb8aa3b, v90
	v_rcp_f32_e32 v88, v88
	v_pk_mul_f32 v[84:85], v[84:85], v[92:93]
	v_rcp_f32_e32 v89, v89
	v_mul_f32_e32 v92, v94, v106
	v_exp_f32_e32 v90, v90
	v_mul_f32_e32 v92, 0xbfb8aa3b, v92
	v_exp_f32_e32 v92, v92
	v_pk_mul_f32 v[80:81], v[80:81], v[106:107] op_sel_hi:[1,0]
	v_pk_mul_f32 v[86:87], v[86:87], v[106:107] op_sel_hi:[1,0]
	v_pk_mul_f32 v[80:81], v[80:81], v[88:89]
	v_add_f32_e32 v89, 1.0, v90
	v_mul_f32_e32 v90, v95, v106
	v_mul_f32_e32 v90, 0xbfb8aa3b, v90
	v_add_f32_e32 v88, 1.0, v92
	v_exp_f32_e32 v92, v90
	v_mul_f32_e32 v90, v91, v106
	v_mul_f32_e32 v90, 0xbfb8aa3b, v90
	v_exp_f32_e32 v91, v90
	v_rcp_f32_e32 v90, v89
	v_add_f32_e32 v89, 1.0, v92
	v_rcp_f32_e32 v88, v88
	v_rcp_f32_e32 v89, v89
	v_add_f32_e32 v91, 1.0, v91
	v_rcp_f32_e32 v91, v91
	v_pk_mul_f32 v[82:83], v[82:83], v[106:107] op_sel_hi:[1,0]
	v_pk_mul_f32 v[86:87], v[86:87], v[88:89]
	v_lshlrev_b64 v[88:89], 10, v[104:105]
	v_pk_mul_f32 v[82:83], v[82:83], v[90:91]
	v_lshl_add_u64 v[92:93], v[130:131], 0, v[88:89]
	v_cmp_lt_i32_e32 vcc, s28, v104
	v_cvt_pk_bf16_f32 v88, v84, v85
	v_cvt_pk_bf16_f32 v89, v86, v87
	v_cvt_pk_bf16_f32 v90, v80, v81
	v_cvt_pk_bf16_f32 v91, v82, v83
	global_store_dwordx4 v[92:93], v[88:91], off
	s_and_saveexec_b64 s[4:5], vcc
	s_xor_b64 s[4:5], exec, s[4:5]
	s_cbranch_execz .LBB0_324
	v_add_u32_e32 v88, 0xffffc020, v140
	v_and_b32_e32 v89, 3, v157
	v_lshrrev_b32_e32 v88, 2, v88
	v_add_u32_e32 v138, 26, v89
	v_mad_u64_u32 v[88:89], s[18:19], v88, 30, v[138:139]
	v_lshlrev_b64 v[88:89], 11, v[88:89]
	v_lshl_add_u64 v[88:89], v[128:129], 0, v[88:89]
	global_store_dwordx4 v[88:89], v[84:87], off
	global_store_dwordx4 v[88:89], v[80:83], off offset:16

.LBB0_329:
	v_mov_b32_e32 v90, v172
	v_or_b32_e32 v88, 48, v140
	v_ashrrev_i32_e32 v89, 31, v88
	s_mov_b64 s[18:19], -1
	s_and_b64 vcc, exec, s[0:1]
	v_cmp_lt_i32_e64 s[4:5], s28, v88
	s_cbranch_vccnz .LBB0_339
	v_add_u32_e32 v138, 0xffffc030, v140
	v_lshlrev_b64 v[92:93], 11, v[138:139]
	v_pk_mul_f32 v[82:83], v[70:71], v[90:91] op_sel_hi:[1,0]
	v_pk_mul_f32 v[80:81], v[68:69], v[90:91] op_sel_hi:[1,0]
	v_pk_mul_f32 v[86:87], v[66:67], v[90:91] op_sel_hi:[1,0]
	v_pk_mul_f32 v[84:85], v[64:65], v[90:91] op_sel_hi:[1,0]
	v_lshl_add_u64 v[92:93], v[146:147], 0, v[92:93]
	s_and_saveexec_b64 s[18:19], s[4:5]
	s_xor_b64 s[18:19], exec, s[18:19]
	s_cbranch_execz .LBB0_332
	global_store_dwordx4 v[92:93], v[80:83], off offset:-4096
	global_store_dwordx4 v[92:93], v[84:87], off offset:-4080

.LBB0_339:
	s_and_b64 vcc, exec, s[18:19]
	s_cbranch_vccz .LBB0_347
	v_mul_f32_e32 v76, v76, v90
	v_mul_f32_e32 v77, v77, v90
	v_mul_f32_e32 v76, 0xbfb8aa3b, v76
	v_mul_f32_e32 v77, 0xbfb8aa3b, v77
	v_exp_f32_e32 v76, v76
	v_exp_f32_e32 v77, v77
	v_mul_f32_e32 v72, v72, v90
	v_mul_f32_e32 v73, v73, v90
	v_mul_f32_e32 v72, 0xbfb8aa3b, v72
	v_mul_f32_e32 v73, 0xbfb8aa3b, v73
	v_exp_f32_e32 v72, v72
	v_add_f32_e32 v76, 1.0, v76
	v_add_f32_e32 v77, 1.0, v77
	v_exp_f32_e32 v73, v73
	v_rcp_f32_e32 v76, v76
	v_rcp_f32_e32 v77, v77
	v_mul_f32_e32 v74, v74, v90
	v_add_f32_e32 v72, 1.0, v72
	v_pk_mul_f32 v[68:69], v[68:69], v[90:91] op_sel_hi:[1,0]
	v_add_f32_e32 v73, 1.0, v73
	v_mul_f32_e32 v74, 0xbfb8aa3b, v74
	v_rcp_f32_e32 v72, v72
	v_pk_mul_f32 v[68:69], v[68:69], v[76:77]
	v_rcp_f32_e32 v73, v73
	v_mul_f32_e32 v76, v78, v90
	v_exp_f32_e32 v74, v74
	v_mul_f32_e32 v76, 0xbfb8aa3b, v76
	v_exp_f32_e32 v76, v76
	v_pk_mul_f32 v[64:65], v[64:65], v[90:91] op_sel_hi:[1,0]
	v_pk_mul_f32 v[70:71], v[70:71], v[90:91] op_sel_hi:[1,0]
	v_pk_mul_f32 v[64:65], v[64:65], v[72:73]
	v_add_f32_e32 v73, 1.0, v74
	v_mul_f32_e32 v74, v79, v90
	v_mul_f32_e32 v74, 0xbfb8aa3b, v74
	v_add_f32_e32 v72, 1.0, v76
	v_exp_f32_e32 v76, v74
	v_mul_f32_e32 v74, v75, v90
	v_mul_f32_e32 v74, 0xbfb8aa3b, v74
	v_exp_f32_e32 v75, v74
	v_rcp_f32_e32 v74, v73
	v_add_f32_e32 v73, 1.0, v76
	v_rcp_f32_e32 v72, v72
	v_rcp_f32_e32 v73, v73
	v_add_f32_e32 v75, 1.0, v75
	v_rcp_f32_e32 v75, v75
	v_pk_mul_f32 v[66:67], v[66:67], v[90:91] op_sel_hi:[1,0]
	v_pk_mul_f32 v[70:71], v[70:71], v[72:73]
	v_lshlrev_b64 v[72:73], 10, v[88:89]
	v_pk_mul_f32 v[66:67], v[66:67], v[74:75]
	v_lshl_add_u64 v[76:77], v[130:131], 0, v[72:73]
	v_cmp_lt_i32_e32 vcc, s28, v88
	v_cvt_pk_bf16_f32 v72, v68, v69
	v_cvt_pk_bf16_f32 v73, v70, v71
	v_cvt_pk_bf16_f32 v74, v64, v65
	v_cvt_pk_bf16_f32 v75, v66, v67
	global_store_dwordx4 v[76:77], v[72:75], off
	s_and_saveexec_b64 s[4:5], vcc
	s_xor_b64 s[4:5], exec, s[4:5]
	s_cbranch_execz .LBB0_342
	v_add_u32_e32 v72, 0xffffc030, v140
	v_and_b32_e32 v73, 3, v157
	v_lshrrev_b32_e32 v72, 2, v72
	v_add_u32_e32 v138, 26, v73
	v_mad_u64_u32 v[72:73], s[18:19], v72, 30, v[138:139]
	v_lshlrev_b64 v[72:73], 11, v[72:73]
	v_lshl_add_u64 v[72:73], v[128:129], 0, v[72:73]
	global_store_dwordx4 v[72:73], v[68:71], off
	global_store_dwordx4 v[72:73], v[64:67], off offset:16

.LBB0_347:
	v_mov_b32_e32 v74, v173
	v_add_u32_e32 v72, 0x80, v140
	v_ashrrev_i32_e32 v73, 31, v72
	s_mov_b64 s[18:19], -1
	s_and_b64 vcc, exec, s[0:1]
	v_cmp_lt_i32_e64 s[4:5], s28, v72
	s_cbranch_vccnz .LBB0_357
	v_add_u32_e32 v138, 0xffffc080, v140
	v_lshlrev_b64 v[76:77], 11, v[138:139]
	v_pk_mul_f32 v[66:67], v[54:55], v[74:75] op_sel_hi:[1,0]
	v_pk_mul_f32 v[64:65], v[52:53], v[74:75] op_sel_hi:[1,0]
	v_pk_mul_f32 v[70:71], v[50:51], v[74:75] op_sel_hi:[1,0]
	v_pk_mul_f32 v[68:69], v[48:49], v[74:75] op_sel_hi:[1,0]
	v_lshl_add_u64 v[76:77], v[146:147], 0, v[76:77]
	s_and_saveexec_b64 s[18:19], s[4:5]
	s_xor_b64 s[18:19], exec, s[18:19]
	s_cbranch_execz .LBB0_350
	global_store_dwordx4 v[76:77], v[64:67], off offset:-4096
	global_store_dwordx4 v[76:77], v[68:71], off offset:-4080

.LBB0_357:
	s_and_b64 vcc, exec, s[18:19]
	s_cbranch_vccz .LBB0_361
	v_mul_f32_e32 v60, v60, v74
	v_mul_f32_e32 v61, v61, v74
	v_mul_f32_e32 v60, 0xbfb8aa3b, v60
	v_mul_f32_e32 v61, 0xbfb8aa3b, v61
	v_exp_f32_e32 v60, v60
	v_exp_f32_e32 v61, v61
	v_mul_f32_e32 v56, v56, v74
	v_mul_f32_e32 v57, v57, v74
	v_mul_f32_e32 v56, 0xbfb8aa3b, v56
	v_mul_f32_e32 v57, 0xbfb8aa3b, v57
	v_exp_f32_e32 v56, v56
	v_add_f32_e32 v60, 1.0, v60
	v_add_f32_e32 v61, 1.0, v61
	v_exp_f32_e32 v57, v57
	v_rcp_f32_e32 v60, v60
	v_rcp_f32_e32 v61, v61
	v_mul_f32_e32 v58, v58, v74
	v_add_f32_e32 v56, 1.0, v56
	v_pk_mul_f32 v[52:53], v[52:53], v[74:75] op_sel_hi:[1,0]
	v_add_f32_e32 v57, 1.0, v57
	v_mul_f32_e32 v58, 0xbfb8aa3b, v58
	v_rcp_f32_e32 v56, v56
	v_pk_mul_f32 v[52:53], v[52:53], v[60:61]
	v_rcp_f32_e32 v57, v57
	v_mul_f32_e32 v60, v62, v74
	v_exp_f32_e32 v58, v58
	v_mul_f32_e32 v60, 0xbfb8aa3b, v60
	v_exp_f32_e32 v60, v60
	v_pk_mul_f32 v[48:49], v[48:49], v[74:75] op_sel_hi:[1,0]
	v_pk_mul_f32 v[54:55], v[54:55], v[74:75] op_sel_hi:[1,0]
	v_pk_mul_f32 v[48:49], v[48:49], v[56:57]
	v_add_f32_e32 v57, 1.0, v58
	v_mul_f32_e32 v58, v63, v74
	v_mul_f32_e32 v58, 0xbfb8aa3b, v58
	v_add_f32_e32 v56, 1.0, v60
	v_exp_f32_e32 v60, v58
	v_mul_f32_e32 v58, v59, v74
	v_mul_f32_e32 v58, 0xbfb8aa3b, v58
	v_exp_f32_e32 v59, v58
	v_rcp_f32_e32 v58, v57
	v_add_f32_e32 v57, 1.0, v60
	v_rcp_f32_e32 v56, v56
	v_rcp_f32_e32 v57, v57
	v_add_f32_e32 v59, 1.0, v59
	v_rcp_f32_e32 v59, v59
	v_pk_mul_f32 v[50:51], v[50:51], v[74:75] op_sel_hi:[1,0]
	v_pk_mul_f32 v[54:55], v[54:55], v[56:57]
	v_lshlrev_b64 v[56:57], 10, v[72:73]
	v_pk_mul_f32 v[50:51], v[50:51], v[58:59]
	v_lshl_add_u64 v[60:61], v[130:131], 0, v[56:57]
	v_cmp_lt_i32_e32 vcc, s28, v72
	v_cvt_pk_bf16_f32 v56, v52, v53
	v_cvt_pk_bf16_f32 v57, v54, v55
	v_cvt_pk_bf16_f32 v58, v48, v49
	v_cvt_pk_bf16_f32 v59, v50, v51
	global_store_dwordx4 v[60:61], v[56:59], off
	s_and_saveexec_b64 s[4:5], vcc
	s_cbranch_execz .LBB0_360
	v_add_u32_e32 v56, 0xffffc080, v140
	v_and_b32_e32 v57, 3, v157
	v_lshrrev_b32_e32 v56, 2, v56
	v_add_u32_e32 v138, 26, v57
	v_mad_u64_u32 v[56:57], s[18:19], v56, 30, v[138:139]
	v_lshlrev_b64 v[56:57], 11, v[56:57]
	v_lshl_add_u64 v[56:57], v[128:129], 0, v[56:57]
	global_store_dwordx4 v[56:57], v[52:55], off
	global_store_dwordx4 v[56:57], v[48:51], off offset:16

.LBB0_361:
	v_mov_b32_e32 v58, v174
	v_add_u32_e32 v56, 0x90, v140
	v_ashrrev_i32_e32 v57, 31, v56
	s_mov_b64 s[18:19], -1
	s_and_b64 vcc, exec, s[0:1]
	v_cmp_lt_i32_e64 s[4:5], s28, v56
	s_cbranch_vccnz .LBB0_371
	v_add_u32_e32 v138, 0xffffc090, v140
	v_lshlrev_b64 v[60:61], 11, v[138:139]
	v_pk_mul_f32 v[50:51], v[38:39], v[58:59] op_sel_hi:[1,0]
	v_pk_mul_f32 v[48:49], v[36:37], v[58:59] op_sel_hi:[1,0]
	v_pk_mul_f32 v[54:55], v[34:35], v[58:59] op_sel_hi:[1,0]
	v_pk_mul_f32 v[52:53], v[32:33], v[58:59] op_sel_hi:[1,0]
	v_lshl_add_u64 v[60:61], v[146:147], 0, v[60:61]
	s_and_saveexec_b64 s[18:19], s[4:5]
	s_xor_b64 s[18:19], exec, s[18:19]
	s_cbranch_execz .LBB0_364
	global_store_dwordx4 v[60:61], v[48:51], off offset:-4096
	global_store_dwordx4 v[60:61], v[52:55], off offset:-4080

.LBB0_371:
	s_and_b64 vcc, exec, s[18:19]
	s_cbranch_vccz .LBB0_375
	v_mul_f32_e32 v44, v44, v58
	v_mul_f32_e32 v45, v45, v58
	v_mul_f32_e32 v44, 0xbfb8aa3b, v44
	v_mul_f32_e32 v45, 0xbfb8aa3b, v45
	v_exp_f32_e32 v44, v44
	v_exp_f32_e32 v45, v45
	v_mul_f32_e32 v40, v40, v58
	v_mul_f32_e32 v41, v41, v58
	v_mul_f32_e32 v40, 0xbfb8aa3b, v40
	v_mul_f32_e32 v41, 0xbfb8aa3b, v41
	v_exp_f32_e32 v40, v40
	v_add_f32_e32 v44, 1.0, v44
	v_add_f32_e32 v45, 1.0, v45
	v_exp_f32_e32 v41, v41
	v_rcp_f32_e32 v44, v44
	v_rcp_f32_e32 v45, v45
	v_mul_f32_e32 v42, v42, v58
	v_add_f32_e32 v40, 1.0, v40
	v_pk_mul_f32 v[36:37], v[36:37], v[58:59] op_sel_hi:[1,0]
	v_add_f32_e32 v41, 1.0, v41
	v_mul_f32_e32 v42, 0xbfb8aa3b, v42
	v_rcp_f32_e32 v40, v40
	v_pk_mul_f32 v[36:37], v[36:37], v[44:45]
	v_rcp_f32_e32 v41, v41
	v_mul_f32_e32 v44, v46, v58
	v_exp_f32_e32 v42, v42
	v_mul_f32_e32 v44, 0xbfb8aa3b, v44
	v_exp_f32_e32 v44, v44
	v_pk_mul_f32 v[32:33], v[32:33], v[58:59] op_sel_hi:[1,0]
	v_pk_mul_f32 v[38:39], v[38:39], v[58:59] op_sel_hi:[1,0]
	v_pk_mul_f32 v[32:33], v[32:33], v[40:41]
	v_add_f32_e32 v41, 1.0, v42
	v_mul_f32_e32 v42, v47, v58
	v_mul_f32_e32 v42, 0xbfb8aa3b, v42
	v_add_f32_e32 v40, 1.0, v44
	v_exp_f32_e32 v44, v42
	v_mul_f32_e32 v42, v43, v58
	v_mul_f32_e32 v42, 0xbfb8aa3b, v42
	v_exp_f32_e32 v43, v42
	v_rcp_f32_e32 v42, v41
	v_add_f32_e32 v41, 1.0, v44
	v_rcp_f32_e32 v40, v40
	v_rcp_f32_e32 v41, v41
	v_add_f32_e32 v43, 1.0, v43
	v_rcp_f32_e32 v43, v43
	v_pk_mul_f32 v[34:35], v[34:35], v[58:59] op_sel_hi:[1,0]
	v_pk_mul_f32 v[38:39], v[38:39], v[40:41]
	v_lshlrev_b64 v[40:41], 10, v[56:57]
	v_pk_mul_f32 v[34:35], v[34:35], v[42:43]
	v_lshl_add_u64 v[44:45], v[130:131], 0, v[40:41]
	v_cmp_lt_i32_e32 vcc, s28, v56
	v_cvt_pk_bf16_f32 v40, v36, v37
	v_cvt_pk_bf16_f32 v41, v38, v39
	v_cvt_pk_bf16_f32 v42, v32, v33
	v_cvt_pk_bf16_f32 v43, v34, v35
	global_store_dwordx4 v[44:45], v[40:43], off
	s_and_saveexec_b64 s[4:5], vcc
	s_cbranch_execz .LBB0_374
	v_add_u32_e32 v40, 0xffffc090, v140
	v_and_b32_e32 v41, 3, v157
	v_lshrrev_b32_e32 v40, 2, v40
	v_add_u32_e32 v138, 26, v41
	v_mad_u64_u32 v[40:41], s[18:19], v40, 30, v[138:139]
	v_lshlrev_b64 v[40:41], 11, v[40:41]
	v_lshl_add_u64 v[40:41], v[128:129], 0, v[40:41]
	global_store_dwordx4 v[40:41], v[36:39], off
	global_store_dwordx4 v[40:41], v[32:35], off offset:16

.LBB0_375:
	v_mov_b32_e32 v42, v175
	v_add_u32_e32 v40, 0xa0, v140
	v_ashrrev_i32_e32 v41, 31, v40
	s_mov_b64 s[18:19], -1
	s_and_b64 vcc, exec, s[0:1]
	v_cmp_lt_i32_e64 s[4:5], s28, v40
	s_cbranch_vccnz .LBB0_385
	v_add_u32_e32 v138, 0xffffc0a0, v140
	v_lshlrev_b64 v[44:45], 11, v[138:139]
	v_pk_mul_f32 v[34:35], v[22:23], v[42:43] op_sel_hi:[1,0]
	v_pk_mul_f32 v[32:33], v[20:21], v[42:43] op_sel_hi:[1,0]
	v_pk_mul_f32 v[38:39], v[18:19], v[42:43] op_sel_hi:[1,0]
	v_pk_mul_f32 v[36:37], v[16:17], v[42:43] op_sel_hi:[1,0]
	v_lshl_add_u64 v[44:45], v[146:147], 0, v[44:45]
	s_and_saveexec_b64 s[18:19], s[4:5]
	s_xor_b64 s[18:19], exec, s[18:19]
	s_cbranch_execz .LBB0_378
	global_store_dwordx4 v[44:45], v[32:35], off offset:-4096
	global_store_dwordx4 v[44:45], v[36:39], off offset:-4080

.LBB0_385:
	s_and_b64 vcc, exec, s[18:19]
	s_cbranch_vccz .LBB0_393
	v_mul_f32_e32 v28, v28, v42
	v_mul_f32_e32 v29, v29, v42
	v_mul_f32_e32 v28, 0xbfb8aa3b, v28
	v_mul_f32_e32 v29, 0xbfb8aa3b, v29
	v_exp_f32_e32 v28, v28
	v_exp_f32_e32 v29, v29
	v_mul_f32_e32 v24, v24, v42
	v_mul_f32_e32 v25, v25, v42
	v_mul_f32_e32 v24, 0xbfb8aa3b, v24
	v_mul_f32_e32 v25, 0xbfb8aa3b, v25
	v_exp_f32_e32 v24, v24
	v_add_f32_e32 v28, 1.0, v28
	v_add_f32_e32 v29, 1.0, v29
	v_exp_f32_e32 v25, v25
	v_rcp_f32_e32 v28, v28
	v_rcp_f32_e32 v29, v29
	v_mul_f32_e32 v26, v26, v42
	v_add_f32_e32 v24, 1.0, v24
	v_pk_mul_f32 v[20:21], v[20:21], v[42:43] op_sel_hi:[1,0]
	v_add_f32_e32 v25, 1.0, v25
	v_mul_f32_e32 v26, 0xbfb8aa3b, v26
	v_rcp_f32_e32 v24, v24
	v_pk_mul_f32 v[20:21], v[20:21], v[28:29]
	v_rcp_f32_e32 v25, v25
	v_mul_f32_e32 v28, v30, v42
	v_exp_f32_e32 v26, v26
	v_mul_f32_e32 v28, 0xbfb8aa3b, v28
	v_exp_f32_e32 v28, v28
	v_pk_mul_f32 v[16:17], v[16:17], v[42:43] op_sel_hi:[1,0]
	v_pk_mul_f32 v[22:23], v[22:23], v[42:43] op_sel_hi:[1,0]
	v_pk_mul_f32 v[16:17], v[16:17], v[24:25]
	v_add_f32_e32 v25, 1.0, v26
	v_mul_f32_e32 v26, v31, v42
	v_mul_f32_e32 v26, 0xbfb8aa3b, v26
	v_add_f32_e32 v24, 1.0, v28
	v_exp_f32_e32 v28, v26
	v_mul_f32_e32 v26, v27, v42
	v_mul_f32_e32 v26, 0xbfb8aa3b, v26
	v_exp_f32_e32 v27, v26
	v_rcp_f32_e32 v26, v25
	v_add_f32_e32 v25, 1.0, v28
	v_rcp_f32_e32 v24, v24
	v_rcp_f32_e32 v25, v25
	v_add_f32_e32 v27, 1.0, v27
	v_rcp_f32_e32 v27, v27
	v_pk_mul_f32 v[18:19], v[18:19], v[42:43] op_sel_hi:[1,0]
	v_pk_mul_f32 v[22:23], v[22:23], v[24:25]
	v_lshlrev_b64 v[24:25], 10, v[40:41]
	v_pk_mul_f32 v[18:19], v[18:19], v[26:27]
	v_lshl_add_u64 v[28:29], v[130:131], 0, v[24:25]
	v_cmp_lt_i32_e32 vcc, s28, v40
	v_cvt_pk_bf16_f32 v24, v20, v21
	v_cvt_pk_bf16_f32 v25, v22, v23
	v_cvt_pk_bf16_f32 v26, v16, v17
	v_cvt_pk_bf16_f32 v27, v18, v19
	global_store_dwordx4 v[28:29], v[24:27], off
	s_and_saveexec_b64 s[4:5], vcc
	s_xor_b64 s[4:5], exec, s[4:5]
	s_cbranch_execz .LBB0_388
	v_add_u32_e32 v24, 0xffffc0a0, v140
	v_and_b32_e32 v25, 3, v157
	v_lshrrev_b32_e32 v24, 2, v24
	v_add_u32_e32 v138, 26, v25
	v_mad_u64_u32 v[24:25], s[18:19], v24, 30, v[138:139]
	v_lshlrev_b64 v[24:25], 11, v[24:25]
	v_lshl_add_u64 v[24:25], v[128:129], 0, v[24:25]
	global_store_dwordx4 v[24:25], v[20:23], off
	global_store_dwordx4 v[24:25], v[16:19], off offset:16

.LBB0_393:
	v_mov_b32_e32 v26, v176
	v_add_u32_e32 v24, 0xb0, v140
	v_ashrrev_i32_e32 v25, 31, v24
	s_mov_b64 s[4:5], -1
	s_and_b64 vcc, exec, s[0:1]
	v_cmp_lt_i32_e64 s[0:1], s28, v24
	s_cbranch_vccnz .LBB0_403
	v_add_u32_e32 v138, 0xffffc0b0, v140
	v_lshlrev_b64 v[28:29], 11, v[138:139]
	v_pk_mul_f32 v[18:19], v[6:7], v[26:27] op_sel_hi:[1,0]
	v_pk_mul_f32 v[16:17], v[4:5], v[26:27] op_sel_hi:[1,0]
	v_pk_mul_f32 v[22:23], v[2:3], v[26:27] op_sel_hi:[1,0]
	v_pk_mul_f32 v[20:21], v[0:1], v[26:27] op_sel_hi:[1,0]
	v_lshl_add_u64 v[30:31], v[146:147], 0, v[28:29]
	s_and_saveexec_b64 s[4:5], s[0:1]
	s_xor_b64 s[4:5], exec, s[4:5]
	s_cbranch_execz .LBB0_396
	global_store_dwordx4 v[30:31], v[16:19], off offset:-4096
	global_store_dwordx4 v[30:31], v[20:23], off offset:-4080

.LBB0_403:
	s_and_b64 vcc, exec, s[4:5]
	s_cbranch_vccz .LBB0_411
	v_mul_f32_e32 v12, v12, v26
	v_mul_f32_e32 v13, v13, v26
	v_mul_f32_e32 v12, 0xbfb8aa3b, v12
	v_mul_f32_e32 v13, 0xbfb8aa3b, v13
	v_exp_f32_e32 v12, v12
	v_exp_f32_e32 v13, v13
	v_mul_f32_e32 v8, v8, v26
	v_mul_f32_e32 v9, v9, v26
	v_mul_f32_e32 v8, 0xbfb8aa3b, v8
	v_mul_f32_e32 v9, 0xbfb8aa3b, v9
	v_exp_f32_e32 v8, v8
	v_add_f32_e32 v12, 1.0, v12
	v_add_f32_e32 v13, 1.0, v13
	v_exp_f32_e32 v9, v9
	v_rcp_f32_e32 v12, v12
	v_rcp_f32_e32 v13, v13
	v_mul_f32_e32 v10, v10, v26
	v_add_f32_e32 v8, 1.0, v8
	v_pk_mul_f32 v[4:5], v[4:5], v[26:27] op_sel_hi:[1,0]
	v_add_f32_e32 v9, 1.0, v9
	v_mul_f32_e32 v10, 0xbfb8aa3b, v10
	v_rcp_f32_e32 v8, v8
	v_pk_mul_f32 v[4:5], v[4:5], v[12:13]
	v_rcp_f32_e32 v9, v9
	v_mul_f32_e32 v12, v14, v26
	v_exp_f32_e32 v10, v10
	v_mul_f32_e32 v12, 0xbfb8aa3b, v12
	v_exp_f32_e32 v12, v12
	v_pk_mul_f32 v[0:1], v[0:1], v[26:27] op_sel_hi:[1,0]
	v_pk_mul_f32 v[6:7], v[6:7], v[26:27] op_sel_hi:[1,0]
	v_pk_mul_f32 v[0:1], v[0:1], v[8:9]
	v_add_f32_e32 v9, 1.0, v10
	v_mul_f32_e32 v10, v15, v26
	v_mul_f32_e32 v10, 0xbfb8aa3b, v10
	v_add_f32_e32 v8, 1.0, v12
	v_exp_f32_e32 v12, v10
	v_mul_f32_e32 v10, v11, v26
	v_mul_f32_e32 v10, 0xbfb8aa3b, v10
	v_exp_f32_e32 v11, v10
	v_rcp_f32_e32 v10, v9
	v_add_f32_e32 v9, 1.0, v12
	v_rcp_f32_e32 v8, v8
	v_rcp_f32_e32 v9, v9
	v_add_f32_e32 v11, 1.0, v11
	v_rcp_f32_e32 v11, v11
	v_pk_mul_f32 v[2:3], v[2:3], v[26:27] op_sel_hi:[1,0]
	v_pk_mul_f32 v[6:7], v[6:7], v[8:9]
	v_lshlrev_b64 v[8:9], 10, v[24:25]
	v_pk_mul_f32 v[2:3], v[2:3], v[10:11]
	v_lshl_add_u64 v[12:13], v[130:131], 0, v[8:9]
	v_cmp_lt_i32_e32 vcc, s28, v24
	v_cvt_pk_bf16_f32 v8, v4, v5
	v_cvt_pk_bf16_f32 v9, v6, v7
	v_cvt_pk_bf16_f32 v10, v0, v1
	v_cvt_pk_bf16_f32 v11, v2, v3
	global_store_dwordx4 v[12:13], v[8:11], off
	s_and_saveexec_b64 s[0:1], vcc
	s_xor_b64 s[0:1], exec, s[0:1]
	s_cbranch_execz .LBB0_406
	v_add_u32_e32 v8, 0xffffc0b0, v140
	v_and_b32_e32 v9, 3, v157
	v_lshrrev_b32_e32 v8, 2, v8
	v_add_u32_e32 v138, 26, v9
	v_mad_u64_u32 v[8:9], s[4:5], v8, 30, v[138:139]
	v_lshlrev_b64 v[8:9], 11, v[8:9]
	v_lshl_add_u64 v[8:9], v[128:129], 0, v[8:9]
	global_store_dwordx4 v[8:9], v[4:7], off
	global_store_dwordx4 v[8:9], v[0:3], off offset:16
